# grid barrier: non-leader workgroups poll the cross-XCC release generation (TOPGEN) directly instead of waiting for their XCC leader to relay it through XGEN (removes one agent-scope round trip per syn
# speedup vs baseline: 1.0005x; 1.0005x over previous
.LBB0_134:
	s_lshl_b32 s24, s42, 6
	s_add_i32 s2, s24, 0x500
	s_mov_b32 s3, 0
	s_lshl_b64 s[0:1], s[2:3], 2
	s_add_u32 s0, s40, s0
	s_addc_u32 s1, s41, s1
	v_mov_b32_e32 v1, 1
	v_mov_b64_e32 v[4:5], s[0:1]
	flat_atomic_add v1, v[4:5], v1 sc0
	v_cvt_f32_u32_e32 v3, v2
	v_sub_u32_e32 v4, 0, v2
	v_rcp_iflag_f32_e32 v3, v3
	s_nop 0
	v_mul_f32_e32 v3, 0x4f7ffffe, v3
	v_cvt_u32_f32_e32 v3, v3
	v_mul_lo_u32 v4, v4, v3
	v_mul_hi_u32 v4, v3, v4
	v_add_u32_e32 v3, v3, v4
	s_waitcnt vmcnt(0) lgkmcnt(0)
	v_mul_hi_u32 v3, v1, v3
	v_mul_lo_u32 v5, v3, v2
	v_add_u32_e32 v4, 1, v1
	v_sub_u32_e32 v1, v1, v5
	v_add_u32_e32 v6, 1, v3
	v_cmp_ge_u32_e32 vcc, v1, v2
	v_sub_u32_e32 v5, v1, v2
	s_nop 0
	v_cndmask_b32_e32 v3, v3, v6, vcc
	v_cndmask_b32_e32 v1, v1, v5, vcc
	v_add_u32_e32 v5, 1, v3
	v_cmp_ge_u32_e32 vcc, v1, v2
	s_nop 1
	v_cndmask_b32_e32 v1, v3, v5, vcc
	v_mad_u64_u32 v[2:3], s[0:1], v2, v1, v[2:3]
	v_cmp_ne_u32_e32 vcc, v4, v2
	s_and_saveexec_b64 s[0:1], vcc
	s_xor_b64 s[0:1], exec, s[0:1]
	s_cbranch_execz .LBB0_147
	s_add_u32 s4, s40, 0x3500
	s_addc_u32 s5, s41, 0
	v_mov_b64_e32 v[2:3], s[4:5]
	flat_load_dword v0, v[2:3] sc1
	s_waitcnt vmcnt(0) lgkmcnt(0)
	v_cmp_eq_u32_e32 vcc, v0, v1
	s_and_saveexec_b64 s[2:3], vcc
	s_cbranch_execz .LBB0_146
	s_mov_b32 s12, 1
	s_mov_b64 s[6:7], 0
	s_branch .LBB0_138

.LBB0_253:
	s_lshl_b32 s14, s14, 6
	s_add_i32 s90, s14, 0x500
	s_lshl_b64 s[0:1], s[90:91], 2
	s_add_u32 s0, s46, s0
	s_addc_u32 s1, s47, s1
	v_mov_b64_e32 v[4:5], s[0:1]
	flat_atomic_add v4, v[4:5], v196 sc0
	v_cvt_f32_u32_e32 v3, v2
	v_sub_u32_e32 v5, 0, v2
	v_rcp_iflag_f32_e32 v3, v3
	s_nop 0
	v_mul_f32_e32 v3, 0x4f7ffffe, v3
	v_cvt_u32_f32_e32 v3, v3
	v_mul_lo_u32 v5, v5, v3
	v_mul_hi_u32 v5, v3, v5
	v_add_u32_e32 v3, v3, v5
	s_waitcnt vmcnt(0) lgkmcnt(0)
	v_mul_hi_u32 v3, v4, v3
	v_mul_lo_u32 v5, v3, v2
	v_sub_u32_e32 v5, v4, v5
	v_cmp_ge_u32_e32 vcc, v5, v2
	v_add_u32_e32 v6, 1, v3
	s_nop 0
	v_cndmask_b32_e32 v3, v3, v6, vcc
	v_sub_u32_e32 v6, v5, v2
	v_cndmask_b32_e32 v5, v5, v6, vcc
	v_cmp_ge_u32_e32 vcc, v5, v2
	v_add_u32_e32 v5, 1, v3
	v_add_u32_e32 v6, 1, v4
	v_cndmask_b32_e32 v3, v3, v5, vcc
	v_mad_u64_u32 v[4:5], s[0:1], v2, v3, v[2:3]
	v_cmp_ne_u32_e32 vcc, v6, v4
	s_and_saveexec_b64 s[0:1], vcc
	s_xor_b64 s[0:1], exec, s[0:1]
	s_cbranch_execz .LBB0_266
	s_add_u32 s4, s46, 0x3500
	s_addc_u32 s5, s47, 0
	v_mov_b64_e32 v[4:5], s[4:5]
	flat_load_dword v0, v[4:5] sc1
	s_waitcnt vmcnt(0) lgkmcnt(0)
	v_cmp_eq_u32_e32 vcc, v0, v3
	s_and_saveexec_b64 s[2:3], vcc
	s_cbranch_execz .LBB0_265
	s_mov_b32 s12, 1
	s_mov_b64 s[6:7], 0
	s_branch .LBB0_257
